# G1 epilogue: dead shuffle-index computations left over from the replaced ds_bpermute removed (12 instructions per butterfly pair, 192 total)
# speedup vs baseline: 1.0011x; 1.0011x over previous
.LBB0_209:
	v_pk_mul_f32 v[180:181], v[144:145], v[144:145]
	v_pk_mul_f32 v[188:189], v[142:143], v[142:143]
	v_mul_f32_e32 v0, v134, v134
	v_pk_mov_b32 v[190:191], v[188:189], v[180:181] op_sel:[1,0]
	v_mov_b32_e32 v189, v181
	v_pk_add_f32 v[180:181], v[190:191], v[188:189]
	v_pk_mul_f32 v[188:189], v[140:141], v[140:141]
	v_pk_mul_f32 v[190:191], v[138:139], v[138:139]
	v_pk_add_f32 v[180:181], v[180:181], v[180:181] op_sel_hi:[0,1]
	v_pk_mov_b32 v[192:193], v[190:191], v[188:189] op_sel:[1,0]
	v_mov_b32_e32 v191, v189
	v_pk_add_f32 v[188:189], v[192:193], v[190:191]
	v_pk_fma_f32 v[190:191], v[134:135], v[134:135], v[0:1] op_sel_hi:[1,1,0]
	v_mul_f32_e32 v0, v136, v136
	v_pk_add_f32 v[188:189], v[188:189], v[188:189] op_sel_hi:[0,1]
	v_pk_fma_f32 v[192:193], v[136:137], v[136:137], v[0:1] op_sel_hi:[1,1,0]
	v_mul_f32_e32 v190, v130, v130
	v_mul_f32_e32 v192, v131, v131
	v_mul_f32_e32 v188, v132, v132
	v_mul_f32_e32 v180, v133, v133
	v_pk_add_f32 v[190:191], v[190:191], v[192:193]
	v_pk_add_f32 v[180:181], v[188:189], v[180:181]
	v_pk_add_f32 v[180:181], v[190:191], v[180:181]
	s_nop 0
	v_add_f32_e32 v0, v180, v181
	v_mov_b32_e32 v179, v0
	s_nop 1
	v_permlane16_swap_b32_e32 v179, v0
	s_waitcnt lgkmcnt(0)
	v_add_f32_e32 v0, v0, v179
	v_mov_b32_e32 v179, v0
	s_nop 1
	v_permlane32_swap_b32_e32 v179, v0
	s_waitcnt lgkmcnt(0)
	v_add_f32_e32 v0, v0, v179
	v_mul_f32_e32 v0, v174, v0
	v_mul_f32_e32 v0, v174, v0
	v_max_f32_e32 v187, 0, v0
	s_mov_b64 s[12:13], -1
	s_and_b64 vcc, exec, s[86:87]
	s_cbranch_vccz .LBB0_211

.LBB0_224:
	v_pk_mul_f32 v[134:135], v[128:129], v[128:129]
	v_pk_mul_f32 v[136:137], v[126:127], v[126:127]
	v_mul_f32_e32 v0, v118, v118
	v_pk_mov_b32 v[138:139], v[136:137], v[134:135] op_sel:[1,0]
	v_mov_b32_e32 v137, v135
	v_pk_add_f32 v[134:135], v[138:139], v[136:137]
	v_pk_mul_f32 v[136:137], v[124:125], v[124:125]
	v_pk_mul_f32 v[138:139], v[122:123], v[122:123]
	v_pk_add_f32 v[134:135], v[134:135], v[134:135] op_sel_hi:[0,1]
	v_pk_mov_b32 v[140:141], v[138:139], v[136:137] op_sel:[1,0]
	v_mov_b32_e32 v139, v137
	v_pk_add_f32 v[136:137], v[140:141], v[138:139]
	v_pk_fma_f32 v[138:139], v[118:119], v[118:119], v[0:1] op_sel_hi:[1,1,0]
	v_mul_f32_e32 v0, v120, v120
	v_pk_add_f32 v[136:137], v[136:137], v[136:137] op_sel_hi:[0,1]
	v_pk_fma_f32 v[140:141], v[120:121], v[120:121], v[0:1] op_sel_hi:[1,1,0]
	v_mul_f32_e32 v138, v114, v114
	v_mul_f32_e32 v140, v115, v115
	v_mul_f32_e32 v136, v116, v116
	v_mul_f32_e32 v134, v117, v117
	v_pk_add_f32 v[138:139], v[138:139], v[140:141]
	v_pk_add_f32 v[134:135], v[136:137], v[134:135]
	v_pk_add_f32 v[134:135], v[138:139], v[134:135]
	s_nop 0
	v_add_f32_e32 v0, v134, v135
	v_mov_b32_e32 v133, v0
	s_nop 1
	v_permlane16_swap_b32_e32 v133, v0
	s_waitcnt lgkmcnt(0)
	v_add_f32_e32 v0, v0, v133
	v_mov_b32_e32 v133, v0
	s_nop 1
	v_permlane32_swap_b32_e32 v133, v0
	s_waitcnt lgkmcnt(0)
	v_add_f32_e32 v0, v0, v133
	v_mul_f32_e32 v0, v174, v0
	v_mul_f32_e32 v0, v174, v0
	v_max_f32_e32 v133, v187, v187
	v_max_f32_e32 v187, v133, v0

.LBB0_241:
	v_pk_mul_f32 v[118:119], v[112:113], v[112:113]
	v_pk_mul_f32 v[120:121], v[110:111], v[110:111]
	v_mul_f32_e32 v0, v102, v102
	v_pk_mov_b32 v[122:123], v[120:121], v[118:119] op_sel:[1,0]
	v_mov_b32_e32 v121, v119
	v_pk_add_f32 v[118:119], v[122:123], v[120:121]
	v_pk_mul_f32 v[120:121], v[108:109], v[108:109]
	v_pk_mul_f32 v[122:123], v[106:107], v[106:107]
	v_pk_add_f32 v[118:119], v[118:119], v[118:119] op_sel_hi:[0,1]
	v_pk_mov_b32 v[124:125], v[122:123], v[120:121] op_sel:[1,0]
	v_mov_b32_e32 v123, v121
	v_pk_add_f32 v[120:121], v[124:125], v[122:123]
	v_pk_fma_f32 v[122:123], v[102:103], v[102:103], v[0:1] op_sel_hi:[1,1,0]
	v_mul_f32_e32 v0, v104, v104
	v_pk_add_f32 v[120:121], v[120:121], v[120:121] op_sel_hi:[0,1]
	v_pk_fma_f32 v[124:125], v[104:105], v[104:105], v[0:1] op_sel_hi:[1,1,0]
	v_mul_f32_e32 v122, v98, v98
	v_mul_f32_e32 v124, v99, v99
	v_mul_f32_e32 v120, v100, v100
	v_mul_f32_e32 v118, v101, v101
	v_pk_add_f32 v[122:123], v[122:123], v[124:125]
	v_pk_add_f32 v[118:119], v[120:121], v[118:119]
	v_pk_add_f32 v[118:119], v[122:123], v[118:119]
	s_nop 0
	v_add_f32_e32 v0, v118, v119
	v_mov_b32_e32 v117, v0
	s_nop 1
	v_permlane16_swap_b32_e32 v117, v0
	s_waitcnt lgkmcnt(0)
	v_add_f32_e32 v0, v0, v117
	v_mov_b32_e32 v117, v0
	s_nop 1
	v_permlane32_swap_b32_e32 v117, v0
	s_waitcnt lgkmcnt(0)
	v_add_f32_e32 v0, v0, v117
	v_mul_f32_e32 v0, v174, v0
	v_mul_f32_e32 v0, v174, v0
	v_max_f32_e32 v117, v187, v187
	v_max_f32_e32 v187, v117, v0

.LBB0_257:
	v_pk_mul_f32 v[102:103], v[96:97], v[96:97]
	v_pk_mul_f32 v[104:105], v[94:95], v[94:95]
	v_mul_f32_e32 v0, v86, v86
	v_pk_mov_b32 v[106:107], v[104:105], v[102:103] op_sel:[1,0]
	v_mov_b32_e32 v105, v103
	v_pk_add_f32 v[102:103], v[106:107], v[104:105]
	v_pk_mul_f32 v[104:105], v[92:93], v[92:93]
	v_pk_mul_f32 v[106:107], v[90:91], v[90:91]
	v_pk_add_f32 v[102:103], v[102:103], v[102:103] op_sel_hi:[0,1]
	v_pk_mov_b32 v[108:109], v[106:107], v[104:105] op_sel:[1,0]
	v_mov_b32_e32 v107, v105
	v_pk_add_f32 v[104:105], v[108:109], v[106:107]
	v_pk_fma_f32 v[106:107], v[86:87], v[86:87], v[0:1] op_sel_hi:[1,1,0]
	v_mul_f32_e32 v0, v88, v88
	v_pk_add_f32 v[104:105], v[104:105], v[104:105] op_sel_hi:[0,1]
	v_pk_fma_f32 v[108:109], v[88:89], v[88:89], v[0:1] op_sel_hi:[1,1,0]
	v_mul_f32_e32 v106, v82, v82
	v_mul_f32_e32 v108, v83, v83
	v_mul_f32_e32 v104, v84, v84
	v_mul_f32_e32 v102, v85, v85
	v_pk_add_f32 v[106:107], v[106:107], v[108:109]
	v_pk_add_f32 v[102:103], v[104:105], v[102:103]
	v_pk_add_f32 v[102:103], v[106:107], v[102:103]
	s_nop 0
	v_add_f32_e32 v0, v102, v103
	v_mov_b32_e32 v101, v0
	s_nop 1
	v_permlane16_swap_b32_e32 v101, v0
	s_waitcnt lgkmcnt(0)
	v_add_f32_e32 v0, v0, v101
	v_mov_b32_e32 v101, v0
	s_nop 1
	v_permlane32_swap_b32_e32 v101, v0
	s_waitcnt lgkmcnt(0)
	v_add_f32_e32 v0, v0, v101
	v_mul_f32_e32 v0, v174, v0
	v_mul_f32_e32 v0, v174, v0
	v_max_f32_e32 v101, v187, v187
	v_max_f32_e32 v187, v101, v0

.LBB0_273:
	v_pk_mul_f32 v[86:87], v[80:81], v[80:81]
	v_pk_mul_f32 v[88:89], v[78:79], v[78:79]
	v_mul_f32_e32 v0, v70, v70
	v_pk_mov_b32 v[90:91], v[88:89], v[86:87] op_sel:[1,0]
	v_mov_b32_e32 v89, v87
	v_pk_add_f32 v[86:87], v[90:91], v[88:89]
	v_pk_mul_f32 v[88:89], v[76:77], v[76:77]
	v_pk_mul_f32 v[90:91], v[74:75], v[74:75]
	v_pk_add_f32 v[86:87], v[86:87], v[86:87] op_sel_hi:[0,1]
	v_pk_mov_b32 v[92:93], v[90:91], v[88:89] op_sel:[1,0]
	v_mov_b32_e32 v91, v89
	v_pk_add_f32 v[88:89], v[92:93], v[90:91]
	v_pk_fma_f32 v[90:91], v[70:71], v[70:71], v[0:1] op_sel_hi:[1,1,0]
	v_mul_f32_e32 v0, v72, v72
	v_pk_add_f32 v[88:89], v[88:89], v[88:89] op_sel_hi:[0,1]
	v_pk_fma_f32 v[92:93], v[72:73], v[72:73], v[0:1] op_sel_hi:[1,1,0]
	v_mul_f32_e32 v90, v66, v66
	v_mul_f32_e32 v92, v67, v67
	v_mul_f32_e32 v88, v68, v68
	v_mul_f32_e32 v86, v69, v69
	v_pk_add_f32 v[90:91], v[90:91], v[92:93]
	v_pk_add_f32 v[86:87], v[88:89], v[86:87]
	v_pk_add_f32 v[86:87], v[90:91], v[86:87]
	s_nop 0
	v_add_f32_e32 v0, v86, v87
	v_mov_b32_e32 v85, v0
	s_nop 1
	v_permlane16_swap_b32_e32 v85, v0
	s_waitcnt lgkmcnt(0)
	v_add_f32_e32 v0, v0, v85
	v_mov_b32_e32 v85, v0
	s_nop 1
	v_permlane32_swap_b32_e32 v85, v0
	s_waitcnt lgkmcnt(0)
	v_add_f32_e32 v0, v0, v85
	v_mul_f32_e32 v0, v174, v0
	v_mul_f32_e32 v0, v174, v0
	v_max_f32_e32 v85, v187, v187
	v_max_f32_e32 v187, v85, v0

.LBB0_289:
	v_pk_mul_f32 v[70:71], v[48:49], v[48:49]
	v_pk_mul_f32 v[72:73], v[46:47], v[46:47]
	v_mul_f32_e32 v0, v38, v38
	v_pk_mov_b32 v[74:75], v[72:73], v[70:71] op_sel:[1,0]
	v_mov_b32_e32 v73, v71
	v_pk_add_f32 v[70:71], v[74:75], v[72:73]
	v_pk_mul_f32 v[72:73], v[44:45], v[44:45]
	v_pk_mul_f32 v[74:75], v[42:43], v[42:43]
	v_pk_add_f32 v[70:71], v[70:71], v[70:71] op_sel_hi:[0,1]
	v_pk_mov_b32 v[76:77], v[74:75], v[72:73] op_sel:[1,0]
	v_mov_b32_e32 v75, v73
	v_pk_add_f32 v[72:73], v[76:77], v[74:75]
	v_pk_fma_f32 v[74:75], v[38:39], v[38:39], v[0:1] op_sel_hi:[1,1,0]
	v_mul_f32_e32 v0, v40, v40
	v_pk_add_f32 v[72:73], v[72:73], v[72:73] op_sel_hi:[0,1]
	v_pk_fma_f32 v[76:77], v[40:41], v[40:41], v[0:1] op_sel_hi:[1,1,0]
	v_mul_f32_e32 v74, v34, v34
	v_mul_f32_e32 v76, v35, v35
	v_mul_f32_e32 v72, v36, v36
	v_mul_f32_e32 v70, v37, v37
	v_pk_add_f32 v[74:75], v[74:75], v[76:77]
	v_pk_add_f32 v[70:71], v[72:73], v[70:71]
	v_pk_add_f32 v[70:71], v[74:75], v[70:71]
	s_nop 0
	v_add_f32_e32 v0, v70, v71
	v_mov_b32_e32 v69, v0
	s_nop 1
	v_permlane16_swap_b32_e32 v69, v0
	s_waitcnt lgkmcnt(0)
	v_add_f32_e32 v0, v0, v69
	v_mov_b32_e32 v69, v0
	s_nop 1
	v_permlane32_swap_b32_e32 v69, v0
	s_waitcnt lgkmcnt(0)
	v_add_f32_e32 v0, v0, v69
	v_mul_f32_e32 v0, v174, v0
	v_mul_f32_e32 v0, v174, v0
	v_max_f32_e32 v69, v187, v187
	v_max_f32_e32 v187, v69, v0

.LBB0_305:
	v_pk_mul_f32 v[38:39], v[32:33], v[32:33]
	v_pk_mul_f32 v[40:41], v[30:31], v[30:31]
	v_mul_f32_e32 v0, v22, v22
	v_pk_mov_b32 v[42:43], v[40:41], v[38:39] op_sel:[1,0]
	v_mov_b32_e32 v41, v39
	v_pk_add_f32 v[38:39], v[42:43], v[40:41]
	v_pk_mul_f32 v[40:41], v[28:29], v[28:29]
	v_pk_mul_f32 v[42:43], v[26:27], v[26:27]
	v_pk_add_f32 v[38:39], v[38:39], v[38:39] op_sel_hi:[0,1]
	v_pk_mov_b32 v[44:45], v[42:43], v[40:41] op_sel:[1,0]
	v_mov_b32_e32 v43, v41
	v_pk_add_f32 v[40:41], v[44:45], v[42:43]
	v_pk_fma_f32 v[42:43], v[22:23], v[22:23], v[0:1] op_sel_hi:[1,1,0]
	v_mul_f32_e32 v0, v24, v24
	v_pk_add_f32 v[40:41], v[40:41], v[40:41] op_sel_hi:[0,1]
	v_pk_fma_f32 v[44:45], v[24:25], v[24:25], v[0:1] op_sel_hi:[1,1,0]
	v_mul_f32_e32 v42, v18, v18
	v_mul_f32_e32 v44, v19, v19
	v_mul_f32_e32 v40, v20, v20
	v_mul_f32_e32 v38, v21, v21
	v_pk_add_f32 v[42:43], v[42:43], v[44:45]
	v_pk_add_f32 v[38:39], v[40:41], v[38:39]
	v_pk_add_f32 v[38:39], v[42:43], v[38:39]
	s_nop 0
	v_add_f32_e32 v0, v38, v39
	v_mov_b32_e32 v37, v0
	s_nop 1
	v_permlane16_swap_b32_e32 v37, v0
	s_waitcnt lgkmcnt(0)
	v_add_f32_e32 v0, v0, v37
	v_mov_b32_e32 v37, v0
	s_nop 1
	v_permlane32_swap_b32_e32 v37, v0
	s_waitcnt lgkmcnt(0)
	v_add_f32_e32 v0, v0, v37
	v_mul_f32_e32 v0, v174, v0
	v_mul_f32_e32 v0, v174, v0
	v_max_f32_e32 v37, v187, v187
	v_max_f32_e32 v187, v37, v0

.LBB0_317:
	s_andn2_b64 vcc, exec, s[2:3]
	s_cbranch_vccnz .LBB0_329
	s_and_b64 vcc, exec, s[10:11]
	s_cbranch_vccnz .LBB0_320
	v_pk_mul_f32 v[22:23], v[16:17], v[16:17]
	v_pk_mul_f32 v[24:25], v[14:15], v[14:15]
	v_mul_f32_e32 v0, v2, v2
	v_pk_mov_b32 v[26:27], v[24:25], v[22:23] op_sel:[1,0]
	v_mov_b32_e32 v25, v23
	v_pk_add_f32 v[22:23], v[26:27], v[24:25]
	v_pk_mul_f32 v[24:25], v[12:13], v[12:13]
	v_pk_mul_f32 v[26:27], v[10:11], v[10:11]
	v_mul_f32_e32 v21, v3, v3
	v_pk_mov_b32 v[28:29], v[26:27], v[24:25] op_sel:[1,0]
	v_mov_b32_e32 v27, v25
	v_pk_add_f32 v[24:25], v[28:29], v[26:27]
	v_pk_add_f32 v[22:23], v[22:23], v[22:23] op_sel:[0,1] op_sel_hi:[1,0]
	v_pk_add_f32 v[24:25], v[24:25], v[24:25] op_sel:[0,1] op_sel_hi:[1,0]
	v_mov_b32_e32 v23, v0
	v_mov_b32_e32 v25, v21
	v_mul_f32_e32 v0, v7, v7
	v_mul_f32_e32 v26, v4, v4
	v_pk_add_f32 v[22:23], v[22:23], v[24:25]
	v_pk_fma_f32 v[24:25], v[6:7], v[6:7], v[0:1] op_sel_hi:[1,1,0]
	v_mul_f32_e32 v0, v9, v9
	v_mul_f32_e32 v28, v5, v5
	v_mov_b32_e32 v25, v26
	v_pk_fma_f32 v[26:27], v[8:9], v[8:9], v[0:1] op_sel_hi:[1,1,0]
	v_mov_b32_e32 v27, v28
	v_pk_add_f32 v[24:25], v[24:25], v[26:27]
	s_nop 0
	v_pk_add_f32 v[22:23], v[22:23], v[24:25]
	s_nop 0
	v_add_f32_e32 v0, v22, v23
	v_mov_b32_e32 v21, v0
	s_nop 1
	v_permlane16_swap_b32_e32 v21, v0
	s_waitcnt lgkmcnt(0)
	v_add_f32_e32 v0, v0, v21
	v_mov_b32_e32 v21, v0
	s_nop 1
	v_permlane32_swap_b32_e32 v21, v0
	s_waitcnt lgkmcnt(0)
	v_add_f32_e32 v0, v0, v21
	v_fmamk_f32 v0, v0, 0x3c800000, v212
	v_mul_f32_e32 v21, 0x4b800000, v0
	v_cmp_gt_f32_e32 vcc, s40, v0
	s_nop 1
	v_cndmask_b32_e32 v0, v0, v21, vcc
	v_rsq_f32_e32 v0, v0
	s_nop 0
	v_mul_f32_e32 v21, 0x45800000, v0
	v_cndmask_b32_e32 v0, v0, v21, vcc
	v_pk_mul_f32 v[14:15], v[14:15], v[0:1] op_sel_hi:[1,0]
	v_pk_mul_f32 v[16:17], v[16:17], v[0:1] op_sel_hi:[1,0]
	v_pk_mul_f32 v[10:11], v[10:11], v[0:1] op_sel_hi:[1,0]
	v_pk_mul_f32 v[12:13], v[12:13], v[0:1] op_sel_hi:[1,0]
	v_pk_mul_f32 v[6:7], v[6:7], v[0:1] op_sel_hi:[1,0]
	v_pk_mul_f32 v[8:9], v[8:9], v[0:1] op_sel_hi:[1,0]
	v_pk_mul_f32 v[2:3], v[2:3], v[0:1] op_sel_hi:[1,0]
	v_pk_mul_f32 v[4:5], v[4:5], v[0:1] op_sel_hi:[1,0]
	s_waitcnt vmcnt(0)
	v_pk_mul_f32 v[16:17], v[64:65], v[16:17]
	v_pk_mul_f32 v[14:15], v[62:63], v[14:15]
	v_pk_mul_f32 v[12:13], v[60:61], v[12:13]
	v_pk_mul_f32 v[10:11], v[58:59], v[10:11]
	v_pk_mul_f32 v[8:9], v[56:57], v[8:9]
	v_pk_mul_f32 v[6:7], v[54:55], v[6:7]
	v_pk_mul_f32 v[4:5], v[52:53], v[4:5]
	v_pk_mul_f32 v[2:3], v[50:51], v[2:3]

.LBB0_322:
	v_readlane_b32 s84, v254, 61
	v_readlane_b32 s85, v254, 62
	s_andn2_b64 vcc, exec, s[26:27]
	s_cbranch_vccnz .LBB0_324
	v_pk_mul_f32 v[22:23], v[16:17], v[16:17]
	v_pk_mul_f32 v[24:25], v[14:15], v[14:15]
	v_mul_f32_e32 v0, v6, v6
	v_pk_mov_b32 v[26:27], v[24:25], v[22:23] op_sel:[1,0]
	v_mov_b32_e32 v25, v23
	v_pk_add_f32 v[22:23], v[26:27], v[24:25]
	v_pk_mul_f32 v[24:25], v[12:13], v[12:13]
	v_pk_mul_f32 v[26:27], v[10:11], v[10:11]
	v_pk_add_f32 v[22:23], v[22:23], v[22:23] op_sel_hi:[0,1]
	v_pk_mov_b32 v[28:29], v[26:27], v[24:25] op_sel:[1,0]
	v_mov_b32_e32 v27, v25
	v_pk_add_f32 v[24:25], v[28:29], v[26:27]
	v_pk_fma_f32 v[26:27], v[6:7], v[6:7], v[0:1] op_sel_hi:[1,1,0]
	v_mul_f32_e32 v0, v8, v8
	v_pk_add_f32 v[24:25], v[24:25], v[24:25] op_sel_hi:[0,1]
	v_pk_fma_f32 v[28:29], v[8:9], v[8:9], v[0:1] op_sel_hi:[1,1,0]
	v_mul_f32_e32 v26, v2, v2
	v_mul_f32_e32 v28, v3, v3
	v_mul_f32_e32 v24, v4, v4
	v_mul_f32_e32 v22, v5, v5
	v_pk_add_f32 v[26:27], v[26:27], v[28:29]
	v_pk_add_f32 v[22:23], v[24:25], v[22:23]
	v_pk_add_f32 v[22:23], v[26:27], v[22:23]
	s_nop 0
	v_add_f32_e32 v0, v22, v23
	v_mov_b32_e32 v21, v0
	s_nop 1
	v_permlane16_swap_b32_e32 v21, v0
	s_waitcnt lgkmcnt(0)
	v_add_f32_e32 v0, v0, v21
	v_mov_b32_e32 v21, v0
	s_nop 1
	v_permlane32_swap_b32_e32 v21, v0
	s_waitcnt lgkmcnt(0)
	v_add_f32_e32 v0, v0, v21
	v_mul_f32_e32 v0, v174, v0
	v_mul_f32_e32 v0, v174, v0
	v_max_f32_e32 v21, v187, v187
	v_max_f32_e32 v187, v21, v0

.LBB0_339:
	v_pk_mul_f32 v[180:181], v[144:145], v[144:145]
	v_pk_mul_f32 v[188:189], v[142:143], v[142:143]
	v_mul_f32_e32 v0, v130, v130
	v_pk_mov_b32 v[190:191], v[188:189], v[180:181] op_sel:[1,0]
	v_mov_b32_e32 v189, v181
	v_pk_add_f32 v[180:181], v[190:191], v[188:189]
	v_pk_mul_f32 v[188:189], v[140:141], v[140:141]
	v_pk_mul_f32 v[190:191], v[138:139], v[138:139]
	v_mul_f32_e32 v179, v131, v131
	v_pk_mov_b32 v[192:193], v[190:191], v[188:189] op_sel:[1,0]
	v_mov_b32_e32 v191, v189
	v_pk_add_f32 v[188:189], v[192:193], v[190:191]
	v_pk_add_f32 v[180:181], v[180:181], v[180:181] op_sel:[0,1] op_sel_hi:[1,0]
	v_pk_add_f32 v[188:189], v[188:189], v[188:189] op_sel:[0,1] op_sel_hi:[1,0]
	v_mov_b32_e32 v181, v0
	v_mov_b32_e32 v189, v179
	v_mul_f32_e32 v0, v135, v135
	v_pk_add_f32 v[180:181], v[180:181], v[188:189]
	v_pk_fma_f32 v[188:189], v[134:135], v[134:135], v[0:1] op_sel_hi:[1,1,0]
	v_mul_f32_e32 v0, v137, v137
	v_mul_f32_e32 v187, v132, v132
	v_mul_f32_e32 v192, v133, v133
	v_pk_fma_f32 v[190:191], v[136:137], v[136:137], v[0:1] op_sel_hi:[1,1,0]
	v_mov_b32_e32 v189, v187
	v_mov_b32_e32 v191, v192
	v_pk_add_f32 v[188:189], v[188:189], v[190:191]
	v_pk_add_f32 v[180:181], v[180:181], v[188:189]
	s_nop 0
	v_add_f32_e32 v0, v180, v181
	v_mov_b32_e32 v179, v0
	s_nop 1
	v_permlane16_swap_b32_e32 v179, v0
	s_waitcnt lgkmcnt(0)
	v_add_f32_e32 v0, v0, v179
	v_mov_b32_e32 v179, v0
	s_nop 1
	v_permlane32_swap_b32_e32 v179, v0
	s_waitcnt lgkmcnt(0)
	v_add_f32_e32 v0, v0, v179
	v_fmamk_f32 v0, v0, 0x3c800000, v212
	v_mul_f32_e32 v179, 0x4b800000, v0
	v_cmp_gt_f32_e32 vcc, s40, v0
	s_nop 1
	v_cndmask_b32_e32 v0, v0, v179, vcc
	v_rsq_f32_e32 v0, v0
	s_nop 0
	v_mul_f32_e32 v179, 0x45800000, v0
	v_cndmask_b32_e32 v0, v0, v179, vcc
	v_pk_mul_f32 v[142:143], v[142:143], v[0:1] op_sel_hi:[1,0]
	v_pk_mul_f32 v[144:145], v[144:145], v[0:1] op_sel_hi:[1,0]
	v_pk_mul_f32 v[138:139], v[138:139], v[0:1] op_sel_hi:[1,0]
	v_pk_mul_f32 v[140:141], v[140:141], v[0:1] op_sel_hi:[1,0]
	v_pk_mul_f32 v[134:135], v[134:135], v[0:1] op_sel_hi:[1,0]
	v_pk_mul_f32 v[136:137], v[136:137], v[0:1] op_sel_hi:[1,0]
	v_pk_mul_f32 v[130:131], v[130:131], v[0:1] op_sel_hi:[1,0]
	v_pk_mul_f32 v[132:133], v[132:133], v[0:1] op_sel_hi:[1,0]
	s_waitcnt vmcnt(0)
	v_pk_mul_f32 v[144:145], v[64:65], v[144:145]
	v_pk_mul_f32 v[142:143], v[62:63], v[142:143]
	v_pk_mul_f32 v[140:141], v[60:61], v[140:141]
	v_pk_mul_f32 v[138:139], v[58:59], v[138:139]
	v_pk_mul_f32 v[136:137], v[56:57], v[136:137]
	v_pk_mul_f32 v[134:135], v[54:55], v[134:135]
	v_pk_mul_f32 v[132:133], v[52:53], v[132:133]
	v_pk_mul_f32 v[130:131], v[50:51], v[130:131]
	s_andn2_b64 vcc, exec, s[84:85]
	s_cbranch_vccnz .LBB0_208

.LBB0_342:
	v_pk_mul_f32 v[134:135], v[128:129], v[128:129]
	v_pk_mul_f32 v[136:137], v[126:127], v[126:127]
	v_mul_f32_e32 v0, v114, v114
	v_pk_mov_b32 v[138:139], v[136:137], v[134:135] op_sel:[1,0]
	v_mov_b32_e32 v137, v135
	v_pk_add_f32 v[134:135], v[138:139], v[136:137]
	v_pk_mul_f32 v[136:137], v[124:125], v[124:125]
	v_pk_mul_f32 v[138:139], v[122:123], v[122:123]
	v_mul_f32_e32 v133, v115, v115
	v_pk_mov_b32 v[140:141], v[138:139], v[136:137] op_sel:[1,0]
	v_mov_b32_e32 v139, v137
	v_pk_add_f32 v[136:137], v[140:141], v[138:139]
	v_pk_add_f32 v[134:135], v[134:135], v[134:135] op_sel:[0,1] op_sel_hi:[1,0]
	v_pk_add_f32 v[136:137], v[136:137], v[136:137] op_sel:[0,1] op_sel_hi:[1,0]
	v_mov_b32_e32 v135, v0
	v_mov_b32_e32 v137, v133
	v_mul_f32_e32 v0, v119, v119
	v_mul_f32_e32 v138, v116, v116
	v_pk_add_f32 v[134:135], v[134:135], v[136:137]
	v_pk_fma_f32 v[136:137], v[118:119], v[118:119], v[0:1] op_sel_hi:[1,1,0]
	v_mul_f32_e32 v0, v121, v121
	v_mul_f32_e32 v140, v117, v117
	v_mov_b32_e32 v137, v138
	v_pk_fma_f32 v[138:139], v[120:121], v[120:121], v[0:1] op_sel_hi:[1,1,0]
	v_mov_b32_e32 v139, v140
	v_pk_add_f32 v[136:137], v[136:137], v[138:139]
	s_nop 0
	v_pk_add_f32 v[134:135], v[134:135], v[136:137]
	s_nop 0
	v_add_f32_e32 v0, v134, v135
	v_mov_b32_e32 v133, v0
	s_nop 1
	v_permlane16_swap_b32_e32 v133, v0
	s_waitcnt lgkmcnt(0)
	v_add_f32_e32 v0, v0, v133
	v_mov_b32_e32 v133, v0
	s_nop 1
	v_permlane32_swap_b32_e32 v133, v0
	s_waitcnt lgkmcnt(0)
	v_add_f32_e32 v0, v0, v133
	v_fmamk_f32 v0, v0, 0x3c800000, v212
	v_mul_f32_e32 v133, 0x4b800000, v0
	v_cmp_gt_f32_e32 vcc, s40, v0
	s_nop 1
	v_cndmask_b32_e32 v0, v0, v133, vcc
	v_rsq_f32_e32 v0, v0
	s_nop 0
	v_mul_f32_e32 v133, 0x45800000, v0
	v_cndmask_b32_e32 v0, v0, v133, vcc
	v_pk_mul_f32 v[126:127], v[126:127], v[0:1] op_sel_hi:[1,0]
	v_pk_mul_f32 v[128:129], v[128:129], v[0:1] op_sel_hi:[1,0]
	v_pk_mul_f32 v[122:123], v[122:123], v[0:1] op_sel_hi:[1,0]
	v_pk_mul_f32 v[124:125], v[124:125], v[0:1] op_sel_hi:[1,0]
	v_pk_mul_f32 v[118:119], v[118:119], v[0:1] op_sel_hi:[1,0]
	v_pk_mul_f32 v[120:121], v[120:121], v[0:1] op_sel_hi:[1,0]
	v_pk_mul_f32 v[114:115], v[114:115], v[0:1] op_sel_hi:[1,0]
	v_pk_mul_f32 v[116:117], v[116:117], v[0:1] op_sel_hi:[1,0]
	s_waitcnt vmcnt(0)
	v_pk_mul_f32 v[128:129], v[64:65], v[128:129]
	v_pk_mul_f32 v[126:127], v[62:63], v[126:127]
	v_pk_mul_f32 v[124:125], v[60:61], v[124:125]
	v_pk_mul_f32 v[122:123], v[58:59], v[122:123]
	v_pk_mul_f32 v[120:121], v[56:57], v[120:121]
	v_pk_mul_f32 v[118:119], v[54:55], v[118:119]
	v_pk_mul_f32 v[116:117], v[52:53], v[116:117]
	v_pk_mul_f32 v[114:115], v[50:51], v[114:115]
	s_andn2_b64 vcc, exec, s[84:85]
	s_cbranch_vccnz .LBB0_223

.LBB0_344:
	v_pk_mul_f32 v[118:119], v[112:113], v[112:113]
	v_pk_mul_f32 v[120:121], v[110:111], v[110:111]
	v_mul_f32_e32 v0, v98, v98
	v_pk_mov_b32 v[122:123], v[120:121], v[118:119] op_sel:[1,0]
	v_mov_b32_e32 v121, v119
	v_pk_add_f32 v[118:119], v[122:123], v[120:121]
	v_pk_mul_f32 v[120:121], v[108:109], v[108:109]
	v_pk_mul_f32 v[122:123], v[106:107], v[106:107]
	v_mul_f32_e32 v117, v99, v99
	v_pk_mov_b32 v[124:125], v[122:123], v[120:121] op_sel:[1,0]
	v_mov_b32_e32 v123, v121
	v_pk_add_f32 v[120:121], v[124:125], v[122:123]
	v_pk_add_f32 v[118:119], v[118:119], v[118:119] op_sel:[0,1] op_sel_hi:[1,0]
	v_pk_add_f32 v[120:121], v[120:121], v[120:121] op_sel:[0,1] op_sel_hi:[1,0]
	v_mov_b32_e32 v119, v0
	v_mov_b32_e32 v121, v117
	v_mul_f32_e32 v0, v103, v103
	v_mul_f32_e32 v122, v100, v100
	v_pk_add_f32 v[118:119], v[118:119], v[120:121]
	v_pk_fma_f32 v[120:121], v[102:103], v[102:103], v[0:1] op_sel_hi:[1,1,0]
	v_mul_f32_e32 v0, v105, v105
	v_mul_f32_e32 v124, v101, v101
	v_mov_b32_e32 v121, v122
	v_pk_fma_f32 v[122:123], v[104:105], v[104:105], v[0:1] op_sel_hi:[1,1,0]
	v_mov_b32_e32 v123, v124
	v_pk_add_f32 v[120:121], v[120:121], v[122:123]
	s_nop 0
	v_pk_add_f32 v[118:119], v[118:119], v[120:121]
	s_nop 0
	v_add_f32_e32 v0, v118, v119
	v_mov_b32_e32 v117, v0
	s_nop 1
	v_permlane16_swap_b32_e32 v117, v0
	s_waitcnt lgkmcnt(0)
	v_add_f32_e32 v0, v0, v117
	v_mov_b32_e32 v117, v0
	s_nop 1
	v_permlane32_swap_b32_e32 v117, v0
	s_waitcnt lgkmcnt(0)
	v_add_f32_e32 v0, v0, v117
	v_fmamk_f32 v0, v0, 0x3c800000, v212
	v_mul_f32_e32 v117, 0x4b800000, v0
	v_cmp_gt_f32_e32 vcc, s40, v0
	s_nop 1
	v_cndmask_b32_e32 v0, v0, v117, vcc
	v_rsq_f32_e32 v0, v0
	s_nop 0
	v_mul_f32_e32 v117, 0x45800000, v0
	v_cndmask_b32_e32 v0, v0, v117, vcc
	v_pk_mul_f32 v[110:111], v[110:111], v[0:1] op_sel_hi:[1,0]
	v_pk_mul_f32 v[112:113], v[112:113], v[0:1] op_sel_hi:[1,0]
	v_pk_mul_f32 v[106:107], v[106:107], v[0:1] op_sel_hi:[1,0]
	v_pk_mul_f32 v[108:109], v[108:109], v[0:1] op_sel_hi:[1,0]
	v_pk_mul_f32 v[102:103], v[102:103], v[0:1] op_sel_hi:[1,0]
	v_pk_mul_f32 v[104:105], v[104:105], v[0:1] op_sel_hi:[1,0]
	v_pk_mul_f32 v[98:99], v[98:99], v[0:1] op_sel_hi:[1,0]
	v_pk_mul_f32 v[100:101], v[100:101], v[0:1] op_sel_hi:[1,0]
	s_waitcnt vmcnt(0)
	v_pk_mul_f32 v[112:113], v[64:65], v[112:113]
	v_pk_mul_f32 v[110:111], v[62:63], v[110:111]
	v_pk_mul_f32 v[108:109], v[60:61], v[108:109]
	v_pk_mul_f32 v[106:107], v[58:59], v[106:107]
	v_pk_mul_f32 v[104:105], v[56:57], v[104:105]
	v_pk_mul_f32 v[102:103], v[54:55], v[102:103]
	v_pk_mul_f32 v[100:101], v[52:53], v[100:101]
	v_pk_mul_f32 v[98:99], v[50:51], v[98:99]
	s_andn2_b64 vcc, exec, s[84:85]
	s_cbranch_vccnz .LBB0_240

.LBB0_346:
	v_pk_mul_f32 v[102:103], v[96:97], v[96:97]
	v_pk_mul_f32 v[104:105], v[94:95], v[94:95]
	v_mul_f32_e32 v0, v82, v82
	v_pk_mov_b32 v[106:107], v[104:105], v[102:103] op_sel:[1,0]
	v_mov_b32_e32 v105, v103
	v_pk_add_f32 v[102:103], v[106:107], v[104:105]
	v_pk_mul_f32 v[104:105], v[92:93], v[92:93]
	v_pk_mul_f32 v[106:107], v[90:91], v[90:91]
	v_mul_f32_e32 v101, v83, v83
	v_pk_mov_b32 v[108:109], v[106:107], v[104:105] op_sel:[1,0]
	v_mov_b32_e32 v107, v105
	v_pk_add_f32 v[104:105], v[108:109], v[106:107]
	v_pk_add_f32 v[102:103], v[102:103], v[102:103] op_sel:[0,1] op_sel_hi:[1,0]
	v_pk_add_f32 v[104:105], v[104:105], v[104:105] op_sel:[0,1] op_sel_hi:[1,0]
	v_mov_b32_e32 v103, v0
	v_mov_b32_e32 v105, v101
	v_mul_f32_e32 v0, v87, v87
	v_mul_f32_e32 v106, v84, v84
	v_pk_add_f32 v[102:103], v[102:103], v[104:105]
	v_pk_fma_f32 v[104:105], v[86:87], v[86:87], v[0:1] op_sel_hi:[1,1,0]
	v_mul_f32_e32 v0, v89, v89
	v_mul_f32_e32 v108, v85, v85
	v_mov_b32_e32 v105, v106
	v_pk_fma_f32 v[106:107], v[88:89], v[88:89], v[0:1] op_sel_hi:[1,1,0]
	v_mov_b32_e32 v107, v108
	v_pk_add_f32 v[104:105], v[104:105], v[106:107]
	s_nop 0
	v_pk_add_f32 v[102:103], v[102:103], v[104:105]
	s_nop 0
	v_add_f32_e32 v0, v102, v103
	v_mov_b32_e32 v101, v0
	s_nop 1
	v_permlane16_swap_b32_e32 v101, v0
	s_waitcnt lgkmcnt(0)
	v_add_f32_e32 v0, v0, v101
	v_mov_b32_e32 v101, v0
	s_nop 1
	v_permlane32_swap_b32_e32 v101, v0
	s_waitcnt lgkmcnt(0)
	v_add_f32_e32 v0, v0, v101
	v_fmamk_f32 v0, v0, 0x3c800000, v212
	v_mul_f32_e32 v101, 0x4b800000, v0
	v_cmp_gt_f32_e32 vcc, s40, v0
	s_nop 1
	v_cndmask_b32_e32 v0, v0, v101, vcc
	v_rsq_f32_e32 v0, v0
	s_nop 0
	v_mul_f32_e32 v101, 0x45800000, v0
	v_cndmask_b32_e32 v0, v0, v101, vcc
	v_pk_mul_f32 v[94:95], v[94:95], v[0:1] op_sel_hi:[1,0]
	v_pk_mul_f32 v[96:97], v[96:97], v[0:1] op_sel_hi:[1,0]
	v_pk_mul_f32 v[90:91], v[90:91], v[0:1] op_sel_hi:[1,0]
	v_pk_mul_f32 v[92:93], v[92:93], v[0:1] op_sel_hi:[1,0]
	v_pk_mul_f32 v[86:87], v[86:87], v[0:1] op_sel_hi:[1,0]
	v_pk_mul_f32 v[88:89], v[88:89], v[0:1] op_sel_hi:[1,0]
	v_pk_mul_f32 v[82:83], v[82:83], v[0:1] op_sel_hi:[1,0]
	v_pk_mul_f32 v[84:85], v[84:85], v[0:1] op_sel_hi:[1,0]
	s_waitcnt vmcnt(0)
	v_pk_mul_f32 v[96:97], v[64:65], v[96:97]
	v_pk_mul_f32 v[94:95], v[62:63], v[94:95]
	v_pk_mul_f32 v[92:93], v[60:61], v[92:93]
	v_pk_mul_f32 v[90:91], v[58:59], v[90:91]
	v_pk_mul_f32 v[88:89], v[56:57], v[88:89]
	v_pk_mul_f32 v[86:87], v[54:55], v[86:87]
	v_pk_mul_f32 v[84:85], v[52:53], v[84:85]
	v_pk_mul_f32 v[82:83], v[50:51], v[82:83]
	s_andn2_b64 vcc, exec, s[84:85]
	s_cbranch_vccnz .LBB0_256

.LBB0_348:
	v_pk_mul_f32 v[86:87], v[80:81], v[80:81]
	v_pk_mul_f32 v[88:89], v[78:79], v[78:79]
	v_mul_f32_e32 v0, v66, v66
	v_pk_mov_b32 v[90:91], v[88:89], v[86:87] op_sel:[1,0]
	v_mov_b32_e32 v89, v87
	v_pk_add_f32 v[86:87], v[90:91], v[88:89]
	v_pk_mul_f32 v[88:89], v[76:77], v[76:77]
	v_pk_mul_f32 v[90:91], v[74:75], v[74:75]
	v_mul_f32_e32 v85, v67, v67
	v_pk_mov_b32 v[92:93], v[90:91], v[88:89] op_sel:[1,0]
	v_mov_b32_e32 v91, v89
	v_pk_add_f32 v[88:89], v[92:93], v[90:91]
	v_pk_add_f32 v[86:87], v[86:87], v[86:87] op_sel:[0,1] op_sel_hi:[1,0]
	v_pk_add_f32 v[88:89], v[88:89], v[88:89] op_sel:[0,1] op_sel_hi:[1,0]
	v_mov_b32_e32 v87, v0
	v_mov_b32_e32 v89, v85
	v_mul_f32_e32 v0, v71, v71
	v_mul_f32_e32 v90, v68, v68
	v_pk_add_f32 v[86:87], v[86:87], v[88:89]
	v_pk_fma_f32 v[88:89], v[70:71], v[70:71], v[0:1] op_sel_hi:[1,1,0]
	v_mul_f32_e32 v0, v73, v73
	v_mul_f32_e32 v92, v69, v69
	v_mov_b32_e32 v89, v90
	v_pk_fma_f32 v[90:91], v[72:73], v[72:73], v[0:1] op_sel_hi:[1,1,0]
	v_mov_b32_e32 v91, v92
	v_pk_add_f32 v[88:89], v[88:89], v[90:91]
	s_nop 0
	v_pk_add_f32 v[86:87], v[86:87], v[88:89]
	s_nop 0
	v_add_f32_e32 v0, v86, v87
	v_mov_b32_e32 v85, v0
	s_nop 1
	v_permlane16_swap_b32_e32 v85, v0
	s_waitcnt lgkmcnt(0)
	v_add_f32_e32 v0, v0, v85
	v_mov_b32_e32 v85, v0
	s_nop 1
	v_permlane32_swap_b32_e32 v85, v0
	s_waitcnt lgkmcnt(0)
	v_add_f32_e32 v0, v0, v85
	v_fmamk_f32 v0, v0, 0x3c800000, v212
	v_mul_f32_e32 v85, 0x4b800000, v0
	v_cmp_gt_f32_e32 vcc, s40, v0
	s_nop 1
	v_cndmask_b32_e32 v0, v0, v85, vcc
	v_rsq_f32_e32 v0, v0
	s_nop 0
	v_mul_f32_e32 v85, 0x45800000, v0
	v_cndmask_b32_e32 v0, v0, v85, vcc
	v_pk_mul_f32 v[78:79], v[78:79], v[0:1] op_sel_hi:[1,0]
	v_pk_mul_f32 v[80:81], v[80:81], v[0:1] op_sel_hi:[1,0]
	v_pk_mul_f32 v[74:75], v[74:75], v[0:1] op_sel_hi:[1,0]
	v_pk_mul_f32 v[76:77], v[76:77], v[0:1] op_sel_hi:[1,0]
	v_pk_mul_f32 v[70:71], v[70:71], v[0:1] op_sel_hi:[1,0]
	v_pk_mul_f32 v[72:73], v[72:73], v[0:1] op_sel_hi:[1,0]
	v_pk_mul_f32 v[66:67], v[66:67], v[0:1] op_sel_hi:[1,0]
	v_pk_mul_f32 v[68:69], v[68:69], v[0:1] op_sel_hi:[1,0]
	s_waitcnt vmcnt(0)
	v_pk_mul_f32 v[80:81], v[64:65], v[80:81]
	v_pk_mul_f32 v[78:79], v[62:63], v[78:79]
	v_pk_mul_f32 v[76:77], v[60:61], v[76:77]
	v_pk_mul_f32 v[74:75], v[58:59], v[74:75]
	v_pk_mul_f32 v[72:73], v[56:57], v[72:73]
	v_pk_mul_f32 v[70:71], v[54:55], v[70:71]
	v_pk_mul_f32 v[68:69], v[52:53], v[68:69]
	v_pk_mul_f32 v[66:67], v[50:51], v[66:67]
	s_andn2_b64 vcc, exec, s[84:85]
	s_cbranch_vccnz .LBB0_272

.LBB0_350:
	v_pk_mul_f32 v[70:71], v[48:49], v[48:49]
	v_pk_mul_f32 v[72:73], v[46:47], v[46:47]
	v_mul_f32_e32 v0, v34, v34
	v_pk_mov_b32 v[74:75], v[72:73], v[70:71] op_sel:[1,0]
	v_mov_b32_e32 v73, v71
	v_pk_add_f32 v[70:71], v[74:75], v[72:73]
	v_pk_mul_f32 v[72:73], v[44:45], v[44:45]
	v_pk_mul_f32 v[74:75], v[42:43], v[42:43]
	v_mul_f32_e32 v69, v35, v35
	v_pk_mov_b32 v[76:77], v[74:75], v[72:73] op_sel:[1,0]
	v_mov_b32_e32 v75, v73
	v_pk_add_f32 v[72:73], v[76:77], v[74:75]
	v_pk_add_f32 v[70:71], v[70:71], v[70:71] op_sel:[0,1] op_sel_hi:[1,0]
	v_pk_add_f32 v[72:73], v[72:73], v[72:73] op_sel:[0,1] op_sel_hi:[1,0]
	v_mov_b32_e32 v71, v0
	v_mov_b32_e32 v73, v69
	v_mul_f32_e32 v0, v39, v39
	v_mul_f32_e32 v74, v36, v36
	v_pk_add_f32 v[70:71], v[70:71], v[72:73]
	v_pk_fma_f32 v[72:73], v[38:39], v[38:39], v[0:1] op_sel_hi:[1,1,0]
	v_mul_f32_e32 v0, v41, v41
	v_mul_f32_e32 v76, v37, v37
	v_mov_b32_e32 v73, v74
	v_pk_fma_f32 v[74:75], v[40:41], v[40:41], v[0:1] op_sel_hi:[1,1,0]
	v_mov_b32_e32 v75, v76
	v_pk_add_f32 v[72:73], v[72:73], v[74:75]
	s_nop 0
	v_pk_add_f32 v[70:71], v[70:71], v[72:73]
	s_nop 0
	v_add_f32_e32 v0, v70, v71
	v_mov_b32_e32 v69, v0
	s_nop 1
	v_permlane16_swap_b32_e32 v69, v0
	s_waitcnt lgkmcnt(0)
	v_add_f32_e32 v0, v0, v69
	v_mov_b32_e32 v69, v0
	s_nop 1
	v_permlane32_swap_b32_e32 v69, v0
	s_waitcnt lgkmcnt(0)
	v_add_f32_e32 v0, v0, v69
	v_fmamk_f32 v0, v0, 0x3c800000, v212
	v_mul_f32_e32 v69, 0x4b800000, v0
	v_cmp_gt_f32_e32 vcc, s40, v0
	s_nop 1
	v_cndmask_b32_e32 v0, v0, v69, vcc
	v_rsq_f32_e32 v0, v0
	s_nop 0
	v_mul_f32_e32 v69, 0x45800000, v0
	v_cndmask_b32_e32 v0, v0, v69, vcc
	v_pk_mul_f32 v[46:47], v[46:47], v[0:1] op_sel_hi:[1,0]
	v_pk_mul_f32 v[48:49], v[48:49], v[0:1] op_sel_hi:[1,0]
	v_pk_mul_f32 v[42:43], v[42:43], v[0:1] op_sel_hi:[1,0]
	v_pk_mul_f32 v[44:45], v[44:45], v[0:1] op_sel_hi:[1,0]
	v_pk_mul_f32 v[38:39], v[38:39], v[0:1] op_sel_hi:[1,0]
	v_pk_mul_f32 v[40:41], v[40:41], v[0:1] op_sel_hi:[1,0]
	v_pk_mul_f32 v[34:35], v[34:35], v[0:1] op_sel_hi:[1,0]
	v_pk_mul_f32 v[36:37], v[36:37], v[0:1] op_sel_hi:[1,0]
	s_waitcnt vmcnt(0)
	v_pk_mul_f32 v[48:49], v[64:65], v[48:49]
	v_pk_mul_f32 v[46:47], v[62:63], v[46:47]
	v_pk_mul_f32 v[44:45], v[60:61], v[44:45]
	v_pk_mul_f32 v[42:43], v[58:59], v[42:43]
	v_pk_mul_f32 v[40:41], v[56:57], v[40:41]
	v_pk_mul_f32 v[38:39], v[54:55], v[38:39]
	v_pk_mul_f32 v[36:37], v[52:53], v[36:37]
	v_pk_mul_f32 v[34:35], v[50:51], v[34:35]
	s_andn2_b64 vcc, exec, s[84:85]
	s_cbranch_vccnz .LBB0_288

.LBB0_352:
	v_pk_mul_f32 v[38:39], v[32:33], v[32:33]
	v_pk_mul_f32 v[40:41], v[30:31], v[30:31]
	v_mul_f32_e32 v0, v18, v18
	v_pk_mov_b32 v[42:43], v[40:41], v[38:39] op_sel:[1,0]
	v_mov_b32_e32 v41, v39
	v_pk_add_f32 v[38:39], v[42:43], v[40:41]
	v_pk_mul_f32 v[40:41], v[28:29], v[28:29]
	v_pk_mul_f32 v[42:43], v[26:27], v[26:27]
	v_mul_f32_e32 v37, v19, v19
	v_pk_mov_b32 v[44:45], v[42:43], v[40:41] op_sel:[1,0]
	v_mov_b32_e32 v43, v41
	v_pk_add_f32 v[40:41], v[44:45], v[42:43]
	v_pk_add_f32 v[38:39], v[38:39], v[38:39] op_sel:[0,1] op_sel_hi:[1,0]
	v_pk_add_f32 v[40:41], v[40:41], v[40:41] op_sel:[0,1] op_sel_hi:[1,0]
	v_mov_b32_e32 v39, v0
	v_mov_b32_e32 v41, v37
	v_mul_f32_e32 v0, v23, v23
	v_mul_f32_e32 v42, v20, v20
	v_pk_add_f32 v[38:39], v[38:39], v[40:41]
	v_pk_fma_f32 v[40:41], v[22:23], v[22:23], v[0:1] op_sel_hi:[1,1,0]
	v_mul_f32_e32 v0, v25, v25
	v_mul_f32_e32 v44, v21, v21
	v_mov_b32_e32 v41, v42
	v_pk_fma_f32 v[42:43], v[24:25], v[24:25], v[0:1] op_sel_hi:[1,1,0]
	v_mov_b32_e32 v43, v44
	v_pk_add_f32 v[40:41], v[40:41], v[42:43]
	s_nop 0
	v_pk_add_f32 v[38:39], v[38:39], v[40:41]
	s_nop 0
	v_add_f32_e32 v0, v38, v39
	v_mov_b32_e32 v37, v0
	s_nop 1
	v_permlane16_swap_b32_e32 v37, v0
	s_waitcnt lgkmcnt(0)
	v_add_f32_e32 v0, v0, v37
	v_mov_b32_e32 v37, v0
	s_nop 1
	v_permlane32_swap_b32_e32 v37, v0
	s_waitcnt lgkmcnt(0)
	v_add_f32_e32 v0, v0, v37
	v_fmamk_f32 v0, v0, 0x3c800000, v212
	v_mul_f32_e32 v37, 0x4b800000, v0
	v_cmp_gt_f32_e32 vcc, s40, v0
	s_nop 1
	v_cndmask_b32_e32 v0, v0, v37, vcc
	v_rsq_f32_e32 v0, v0
	s_nop 0
	v_mul_f32_e32 v37, 0x45800000, v0
	v_cndmask_b32_e32 v0, v0, v37, vcc
	v_pk_mul_f32 v[30:31], v[30:31], v[0:1] op_sel_hi:[1,0]
	v_pk_mul_f32 v[32:33], v[32:33], v[0:1] op_sel_hi:[1,0]
	v_pk_mul_f32 v[26:27], v[26:27], v[0:1] op_sel_hi:[1,0]
	v_pk_mul_f32 v[28:29], v[28:29], v[0:1] op_sel_hi:[1,0]
	v_pk_mul_f32 v[22:23], v[22:23], v[0:1] op_sel_hi:[1,0]
	v_pk_mul_f32 v[24:25], v[24:25], v[0:1] op_sel_hi:[1,0]
	v_pk_mul_f32 v[18:19], v[18:19], v[0:1] op_sel_hi:[1,0]
	v_pk_mul_f32 v[20:21], v[20:21], v[0:1] op_sel_hi:[1,0]
	s_waitcnt vmcnt(0)
	v_pk_mul_f32 v[32:33], v[64:65], v[32:33]
	v_pk_mul_f32 v[30:31], v[62:63], v[30:31]
	v_pk_mul_f32 v[28:29], v[60:61], v[28:29]
	v_pk_mul_f32 v[26:27], v[58:59], v[26:27]
	v_pk_mul_f32 v[24:25], v[56:57], v[24:25]
	v_pk_mul_f32 v[22:23], v[54:55], v[22:23]
	v_pk_mul_f32 v[20:21], v[52:53], v[20:21]
	v_pk_mul_f32 v[18:19], v[50:51], v[18:19]
	s_andn2_b64 vcc, exec, s[84:85]
	s_cbranch_vccnz .LBB0_304
